# MLA loop v2: LDS addresses hoisted out of the loop with immediate buffer offsets, first K reads before the bias MFMA, K/V tile staging (LDS writes + next global loads) moved inside the MFMA stream so
# speedup vs baseline: 1.0180x; 1.0180x over previous
.LBB0_436:
	s_or_b64 exec, exec, s[78:79]
	v_or_b32_e32 v16, 2, v171
	v_ashrrev_i32_e32 v21, 7, v18
	v_lshrrev_b32_e32 v18, 1, v18
	v_or_b32_e32 v17, 4, v171
	v_bitop3_b32 v16, v16, v18, 7 bitop3:0x78
	v_or_b32_e32 v20, 6, v171
	v_lshlrev_b32_e32 v200, 4, v16
	v_bitop3_b32 v16, v17, v18, 7 bitop3:0x78
	s_lshl_b32 s70, s18, 2
	v_lshlrev_b32_e32 v198, 7, v19
	v_bitop3_b32 v19, v171, v18, 7 bitop3:0x78
	v_lshlrev_b32_e32 v201, 4, v16
	v_bitop3_b32 v16, v20, v18, 7 bitop3:0x78
	v_add3_u32 v197, v21, s70, 1
	v_lshlrev_b32_e32 v199, 4, v19
	v_lshlrev_b32_e32 v202, 4, v16
	v_mov_b64_e32 v[30:31], v[14:15]
	v_mov_b64_e32 v[46:47], v[14:15]
	s_lshl_b32 s5, s19, 6
	s_add_i32 s70, s70, 4
	s_mov_b32 s73, 0
	v_mov_b32_e32 v203, 0
	s_movk_i32 s14, 0xc0
	s_movk_i32 s71, 0x2000
	s_movk_i32 s72, 0x4000
	v_mov_b32_e32 v153, 0
	v_mov_b32_e32 v154, 0
	v_mov_b32_e32 v155, 0
	v_mov_b64_e32 v[28:29], v[12:13]
	v_mov_b64_e32 v[26:27], v[10:11]
	v_mov_b64_e32 v[24:25], v[8:9]
	v_mov_b64_e32 v[22:23], v[6:7]
	v_mov_b64_e32 v[20:21], v[4:5]
	v_mov_b64_e32 v[18:19], v[2:3]
	v_mov_b64_e32 v[16:17], v[0:1]
	v_mov_b64_e32 v[44:45], v[12:13]
	v_mov_b64_e32 v[42:43], v[10:11]
	v_mov_b64_e32 v[40:41], v[8:9]
	v_mov_b64_e32 v[38:39], v[6:7]
	v_mov_b64_e32 v[36:37], v[4:5]
	v_mov_b64_e32 v[34:35], v[2:3]
	v_mov_b64_e32 v[32:33], v[0:1]
	v_or_b32_e32 v186, v186, v194
	v_or_b32_e32 v184, v184, v194
	v_or_b32_e32 v183, v183, v194
	v_or_b32_e32 v191, v191, v194
	v_or_b32_e32 v190, v190, v194
	v_or_b32_e32 v187, v187, v194
	v_add_u32_e32 v199, v198, v199
	v_add_u32_e32 v200, v198, v200
	v_add_u32_e32 v201, v198, v201
	v_add_u32_e32 v202, v198, v202
.LBB0_437:
	s_mov_b32 s98, 0
	s_and_b32 s68, s73, 1
	s_add_i32 s74, s73, 1
	s_lshl_b32 s69, s68, 13
	v_cmp_ge_i32_e32 vcc, s74, v197
	s_and_saveexec_b64 s[18:19], vcc
	s_xor_b64 s[86:87], exec, s[18:19]
	s_cbranch_execz .LBB0_445
	v_cmp_lt_i32_e32 vcc, s73, v197
	s_and_saveexec_b64 s[78:79], vcc
	s_cbranch_execz .LBB0_444
	v_max_f32_e32 v80, v65, v65
	v_max_f32_e32 v81, v64, v64
	v_max_f32_e32 v80, v81, v80
	v_max3_f32 v80, v80, v66, v67
	v_max3_f32 v80, v80, v68, v69
	v_max3_f32 v80, v80, v70, v71
	v_max3_f32 v80, v80, v72, v73
	v_max3_f32 v80, v80, v74, v75
	v_max3_f32 v80, v80, v76, v77
	v_max3_f32 v80, v80, v78, v79
	v_max3_f32 v80, v80, v48, v49
	v_max3_f32 v80, v80, v50, v51
	v_max3_f32 v80, v80, v52, v53
	v_max3_f32 v80, v80, v54, v55
	v_max3_f32 v80, v80, v56, v57
	v_max3_f32 v80, v80, v58, v59
	v_max3_f32 v80, v80, v60, v61
	s_cmp_eq_u32 s73, 0
	v_max3_f32 v80, v80, v62, v63
	s_cselect_b64 s[18:19], -1, 0
	v_cmp_lt_f32_e32 vcc, s29, v80
	s_or_b64 vcc, s[18:19], vcc
	s_cbranch_vccz .LBB0_443
	v_and_b32_e32 v82, 64, v172
	v_xor_b32_e32 v81, 32, v172
	v_add_u32_e32 v82, 64, v82
	v_cmp_lt_i32_e32 vcc, v81, v82
	v_mov_b32_e32 v155, 0
	s_nop 0
	v_cndmask_b32_e32 v81, v172, v81, vcc
	v_lshlrev_b32_e32 v81, 2, v81
	ds_bpermute_b32 v81, v81, v80
	v_max_f32_e32 v80, v80, v80
	s_waitcnt lgkmcnt(0)
	v_max_f32_e32 v81, v81, v81
	v_max_f32_e32 v81, v80, v81
	v_cmp_lt_f32_e32 vcc, s30, v81
	s_and_b64 s[18:19], s[18:19], vcc
	v_cmp_lt_f32_e32 vcc, s29, v81
	s_or_b64 vcc, vcc, s[18:19]
	v_mov_b32_e32 v80, 0
	s_and_saveexec_b64 s[18:19], vcc
	v_add_f32_e32 v80, v203, v81
	v_cvt_pk_bf16_f32 v80, v80, 0
	v_lshlrev_b32_e32 v81, 16, v80
	v_sub_f32_e32 v80, v81, v203
	v_mov_b32_e32 v203, v81
	s_or_b64 exec, exec, s[18:19]
	v_exp_f32_e64 v82, -v80
	s_mov_b64 vcc, s[8:9]
	v_sub_f32_e32 v79, v79, v80
	v_sub_f32_e32 v78, v78, v80
	v_sub_f32_e32 v77, v77, v80
	v_sub_f32_e32 v76, v76, v80
	v_sub_f32_e32 v75, v75, v80
	v_sub_f32_e32 v74, v74, v80
	v_sub_f32_e32 v73, v73, v80
	v_sub_f32_e32 v72, v72, v80
	v_sub_f32_e32 v71, v71, v80
	v_sub_f32_e32 v70, v70, v80
	v_sub_f32_e32 v69, v69, v80
	v_sub_f32_e32 v68, v68, v80
	v_sub_f32_e32 v67, v67, v80
	v_sub_f32_e32 v66, v66, v80
	v_sub_f32_e32 v65, v65, v80
	v_sub_f32_e32 v64, v64, v80
	v_sub_f32_e32 v63, v63, v80
	v_sub_f32_e32 v62, v62, v80
	v_sub_f32_e32 v61, v61, v80
	v_sub_f32_e32 v60, v60, v80
	v_sub_f32_e32 v59, v59, v80
	v_sub_f32_e32 v58, v58, v80
	v_sub_f32_e32 v57, v57, v80
	v_sub_f32_e32 v56, v56, v80
	v_sub_f32_e32 v55, v55, v80
	v_sub_f32_e32 v54, v54, v80
	v_sub_f32_e32 v53, v53, v80
	v_sub_f32_e32 v52, v52, v80
	v_sub_f32_e32 v51, v51, v80
	v_sub_f32_e32 v50, v50, v80
	v_sub_f32_e32 v49, v49, v80
	v_sub_f32_e32 v48, v48, v80
	v_xor_b32_e32 v80, 0x80000000, v203
	v_pk_mul_f32 v[46:47], v[46:47], v[82:83] op_sel_hi:[1,0]
	v_pk_mul_f32 v[44:45], v[44:45], v[82:83] op_sel_hi:[1,0]
	v_pk_mul_f32 v[42:43], v[42:43], v[82:83] op_sel_hi:[1,0]
	v_pk_mul_f32 v[40:41], v[40:41], v[82:83] op_sel_hi:[1,0]
	v_pk_mul_f32 v[38:39], v[38:39], v[82:83] op_sel_hi:[1,0]
	v_pk_mul_f32 v[36:37], v[36:37], v[82:83] op_sel_hi:[1,0]
	v_pk_mul_f32 v[34:35], v[34:35], v[82:83] op_sel_hi:[1,0]
	v_pk_mul_f32 v[32:33], v[32:33], v[82:83] op_sel_hi:[1,0]
	v_pk_mul_f32 v[30:31], v[30:31], v[82:83] op_sel_hi:[1,0]
	v_pk_mul_f32 v[28:29], v[28:29], v[82:83] op_sel_hi:[1,0]
	v_pk_mul_f32 v[26:27], v[26:27], v[82:83] op_sel_hi:[1,0]
	v_pk_mul_f32 v[24:25], v[24:25], v[82:83] op_sel_hi:[1,0]
	v_pk_mul_f32 v[22:23], v[22:23], v[82:83] op_sel_hi:[1,0]
	v_pk_mul_f32 v[20:21], v[20:21], v[82:83] op_sel_hi:[1,0]
	v_pk_mul_f32 v[18:19], v[18:19], v[82:83] op_sel_hi:[1,0]
	v_pk_mul_f32 v[16:17], v[16:17], v[82:83] op_sel_hi:[1,0]
	v_pk_mul_f32 v[14:15], v[14:15], v[82:83] op_sel_hi:[1,0]
	v_pk_mul_f32 v[12:13], v[12:13], v[82:83] op_sel_hi:[1,0]
	v_pk_mul_f32 v[10:11], v[10:11], v[82:83] op_sel_hi:[1,0]
	v_pk_mul_f32 v[8:9], v[8:9], v[82:83] op_sel_hi:[1,0]
	v_pk_mul_f32 v[6:7], v[6:7], v[82:83] op_sel_hi:[1,0]
	v_pk_mul_f32 v[4:5], v[4:5], v[82:83] op_sel_hi:[1,0]
	v_pk_mul_f32 v[2:3], v[2:3], v[82:83] op_sel_hi:[1,0]
	v_pk_mul_f32 v[0:1], v[0:1], v[82:83] op_sel_hi:[1,0]
	v_cndmask_b32_sdwa v152, v113, v80, vcc dst_sel:DWORD dst_unused:UNUSED_PAD src0_sel:DWORD src1_sel:WORD_1
	v_mov_b32_e32 v154, 0
	v_mov_b32_e32 v153, 0
.LBB0_443:
	s_nop 0
	v_add_u32_e32 v101, s69, v199
	ds_read_b128 v[96:99], v101 offset:32768
	v_exp_f32_e32 v76, v76
	v_exp_f32_e32 v60, v60
	v_exp_f32_e32 v77, v77
	v_exp_f32_e32 v61, v61
	v_exp_f32_e32 v78, v78
	v_exp_f32_e32 v62, v62
	v_exp_f32_e32 v79, v79
	v_exp_f32_e32 v63, v63
	v_exp_f32_e32 v64, v64
	v_exp_f32_e32 v65, v65
	v_exp_f32_e32 v66, v66
	v_exp_f32_e32 v67, v67
	v_exp_f32_e32 v68, v68
	v_exp_f32_e32 v69, v69
	v_exp_f32_e32 v70, v70
	v_exp_f32_e32 v71, v71
	v_pk_add_f32 v[92:93], v[60:61], v[76:77]
	v_pk_add_f32 v[94:95], v[62:63], v[78:79]
	v_pk_add_f32 v[12:13], v[92:93], v[12:13]
	v_pk_add_f32 v[14:15], v[94:95], v[14:15]
	v_cvt_pk_bf16_f32 v92, v64, v65
	v_cvt_pk_bf16_f32 v93, v66, v67
	v_cvt_pk_bf16_f32 v94, v68, v69
	v_cvt_pk_bf16_f32 v95, v70, v71
	v_exp_f32_e32 v72, v72
	v_exp_f32_e32 v56, v56
	s_waitcnt lgkmcnt(0)
	v_mfma_f32_32x32x16_bf16 v[32:47], v[96:99], v[92:95], v[32:47]
	ds_read_b128 v[96:99], v101 offset:36864
	v_exp_f32_e32 v73, v73
	v_exp_f32_e32 v57, v57
	v_exp_f32_e32 v74, v74
	v_exp_f32_e32 v58, v58
	v_exp_f32_e32 v75, v75
	v_exp_f32_e32 v59, v59
	s_waitcnt lgkmcnt(0)
	v_mfma_f32_32x32x16_bf16 v[16:31], v[96:99], v[92:95], v[16:31]
	v_add_u32_e32 v96, s69, v200
	ds_read_b128 v[92:95], v96 offset:32768
	v_add_f32_e64 v88, v56, v72
	v_add_f32_e64 v89, v57, v73
	v_add_f32_e64 v90, v58, v74
	v_add_f32_e64 v91, v59, v75
	v_pk_add_f32 v[8:9], v[88:89], v[8:9]
	v_pk_add_f32 v[10:11], v[90:91], v[10:11]
	v_cvt_pk_bf16_f32 v88, v72, v73
	v_cvt_pk_bf16_f32 v89, v74, v75
	v_cvt_pk_bf16_f32 v90, v76, v77
	v_cvt_pk_bf16_f32 v91, v78, v79
	v_exp_f32_e32 v52, v52
	v_exp_f32_e32 v53, v53
	s_waitcnt lgkmcnt(0)
	v_mfma_f32_32x32x16_bf16 v[32:47], v[92:95], v[88:91], v[32:47]
	ds_read_b128 v[92:95], v96 offset:36864
	v_exp_f32_e32 v54, v54
	v_exp_f32_e32 v55, v55
	v_exp_f32_e32 v48, v48
	v_exp_f32_e32 v49, v49
	v_exp_f32_e32 v50, v50
	v_exp_f32_e32 v51, v51
	s_waitcnt lgkmcnt(0)
	v_mfma_f32_32x32x16_bf16 v[16:31], v[92:95], v[88:91], v[16:31]
	v_add_u32_e32 v92, s69, v201
	ds_read_b128 v[88:91], v92 offset:32768
	v_add_f32_e64 v84, v52, v68
	v_add_f32_e64 v85, v53, v69
	v_add_f32_e64 v86, v54, v70
	v_add_f32_e64 v87, v55, v71
	v_pk_add_f32 v[4:5], v[84:85], v[4:5]
	v_pk_add_f32 v[6:7], v[86:87], v[6:7]
	v_cvt_pk_bf16_f32 v84, v48, v49
	v_cvt_pk_bf16_f32 v85, v50, v51
	v_cvt_pk_bf16_f32 v86, v52, v53
	v_cvt_pk_bf16_f32 v87, v54, v55
	v_pk_add_f32 v[80:81], v[48:49], v[64:65]
	v_pk_add_f32 v[82:83], v[50:51], v[66:67]
	s_waitcnt lgkmcnt(0)
	v_mfma_f32_32x32x16_bf16 v[32:47], v[88:91], v[84:87], v[32:47]
	ds_read_b128 v[88:91], v92 offset:36864
	v_add_f32_e64 v2, v82, v2
	v_add_f32_e64 v3, v83, v3
	v_add_f32_e64 v0, v80, v0
	v_add_f32_e64 v1, v81, v1
	v_cvt_pk_bf16_f32 v80, v56, v57
	v_cvt_pk_bf16_f32 v81, v58, v59
	v_cvt_pk_bf16_f32 v82, v60, v61
	v_cvt_pk_bf16_f32 v83, v62, v63
	s_waitcnt lgkmcnt(0)
	v_mfma_f32_32x32x16_bf16 v[16:31], v[88:91], v[84:87], v[16:31]
	v_add_u32_e32 v88, s69, v202
	ds_read_b128 v[84:87], v88 offset:32768
	s_waitcnt lgkmcnt(0)
	v_mfma_f32_32x32x16_bf16 v[32:47], v[84:87], v[80:83], v[32:47]
	ds_read_b128 v[84:87], v88 offset:36864
	s_waitcnt lgkmcnt(0)
	v_mfma_f32_32x32x16_bf16 v[16:31], v[84:87], v[80:83], v[16:31]

.LBB0_445:
	s_andn2_saveexec_b64 s[86:87], s[86:87]
	s_cbranch_execz .LBB0_456
	ds_read_b128 v[174:177], v186 offset:16384
	ds_read_b128 v[204:207], v186 offset:24576
	v_mfma_f32_32x32x16_bf16 v[80:95], v[112:115], v[152:155], 0
	ds_read_b128 v[208:211], v184 offset:16384
	ds_read_b128 v[212:215], v184 offset:24576
	ds_read_b128 v[216:219], v183 offset:16384
	ds_read_b128 v[220:223], v183 offset:24576
	ds_read_b128 v[230:233], v191 offset:16384
	ds_read_b128 v[234:237], v191 offset:24576
	ds_read_b128 v[238:241], v190 offset:16384
	ds_read_b128 v[242:245], v190 offset:24576
	ds_read_b128 v[246:249], v187 offset:16384
	ds_read_b128 v[250:253], v187 offset:24576
	s_cmp_eq_u32 s73, 0
	s_cselect_b64 s[78:79], -1, 0
	v_max_f32_e32 v224, v65, v65
	v_max_f32_e32 v225, v64, v64
	v_max_f32_e32 v224, v225, v224
	v_max3_f32 v224, v224, v66, v67
	v_max3_f32 v224, v224, v68, v69
	s_waitcnt lgkmcnt(11)
	v_mfma_f32_32x32x16_bf16 v[96:111], v[174:177], v[116:119], v[80:95]
	v_max3_f32 v224, v224, v70, v71
	v_max3_f32 v224, v224, v72, v73
	v_max3_f32 v224, v224, v74, v75
	v_max3_f32 v224, v224, v76, v77
	v_max3_f32 v224, v224, v78, v79
	v_max3_f32 v224, v224, v48, v49
	s_waitcnt lgkmcnt(10)
	v_mfma_f32_32x32x16_bf16 v[80:95], v[204:207], v[116:119], v[80:95]
	ds_read_b128 v[174:177], v199 offset:32768
	v_max3_f32 v224, v224, v50, v51
	v_max3_f32 v224, v224, v52, v53
	v_max3_f32 v224, v224, v54, v55
	v_max3_f32 v224, v224, v56, v57
	v_max3_f32 v224, v224, v58, v59
	v_max3_f32 v224, v224, v60, v61
	v_max3_f32 v229, v224, v62, v63
	v_cmp_lt_f32_e32 vcc, s29, v229
	s_or_b64 vcc, s[78:79], vcc
	s_waitcnt lgkmcnt(10)
	v_mfma_f32_32x32x16_bf16 v[96:111], v[208:211], v[120:123], v[96:111]
	ds_read_b128 v[204:207], v199 offset:36864
	s_cbranch_vccz .LBB0_450
	v_and_b32_e32 v153, 64, v172
	v_xor_b32_e32 v152, 32, v172
	v_add_u32_e32 v153, 64, v153
	v_cmp_lt_i32_e32 vcc, v152, v153
	v_max_f32_e32 v153, v229, v229
	v_mov_b32_e32 v155, 0
	v_cndmask_b32_e32 v152, v172, v152, vcc
	v_lshlrev_b32_e32 v152, 2, v152
	ds_bpermute_b32 v152, v152, v229
	v_mov_b32_e32 v229, 0
	s_waitcnt lgkmcnt(0)
	v_max_f32_e32 v152, v152, v152
	v_max_f32_e32 v152, v153, v152
	v_cmp_lt_f32_e32 vcc, s30, v152
	s_and_b64 s[18:19], s[78:79], vcc
	v_cmp_lt_f32_e32 vcc, s29, v152
	s_or_b64 s[78:79], vcc, s[18:19]
	s_and_saveexec_b64 s[18:19], s[78:79]
	v_add_f32_e32 v152, v203, v152
	v_cvt_pk_bf16_f32 v152, v152, 0
	v_lshlrev_b32_e32 v152, 16, v152
	v_sub_f32_e32 v229, v152, v203
	v_mov_b32_e32 v203, v152
	s_or_b64 exec, exec, s[18:19]
	v_exp_f32_e64 v152, -v229
	s_mov_b64 vcc, s[8:9]
	v_sub_f32_e32 v64, v64, v229
	v_sub_f32_e32 v65, v65, v229
	v_pk_mul_f32 v[46:47], v[46:47], v[152:153] op_sel_hi:[1,0]
	v_pk_mul_f32 v[44:45], v[44:45], v[152:153] op_sel_hi:[1,0]
	v_pk_mul_f32 v[42:43], v[42:43], v[152:153] op_sel_hi:[1,0]
	v_pk_mul_f32 v[40:41], v[40:41], v[152:153] op_sel_hi:[1,0]
	v_pk_mul_f32 v[38:39], v[38:39], v[152:153] op_sel_hi:[1,0]
	v_pk_mul_f32 v[36:37], v[36:37], v[152:153] op_sel_hi:[1,0]
	v_pk_mul_f32 v[34:35], v[34:35], v[152:153] op_sel_hi:[1,0]
	v_pk_mul_f32 v[32:33], v[32:33], v[152:153] op_sel_hi:[1,0]
	v_pk_mul_f32 v[30:31], v[30:31], v[152:153] op_sel_hi:[1,0]
	v_pk_mul_f32 v[28:29], v[28:29], v[152:153] op_sel_hi:[1,0]
	v_pk_mul_f32 v[26:27], v[26:27], v[152:153] op_sel_hi:[1,0]
	v_pk_mul_f32 v[24:25], v[24:25], v[152:153] op_sel_hi:[1,0]
	v_pk_mul_f32 v[22:23], v[22:23], v[152:153] op_sel_hi:[1,0]
	v_pk_mul_f32 v[20:21], v[20:21], v[152:153] op_sel_hi:[1,0]
	v_pk_mul_f32 v[18:19], v[18:19], v[152:153] op_sel_hi:[1,0]
	v_pk_mul_f32 v[16:17], v[16:17], v[152:153] op_sel_hi:[1,0]
	v_pk_mul_f32 v[14:15], v[14:15], v[152:153] op_sel_hi:[1,0]
	v_pk_mul_f32 v[12:13], v[12:13], v[152:153] op_sel_hi:[1,0]
	v_pk_mul_f32 v[10:11], v[10:11], v[152:153] op_sel_hi:[1,0]
	v_pk_mul_f32 v[8:9], v[8:9], v[152:153] op_sel_hi:[1,0]
	v_pk_mul_f32 v[6:7], v[6:7], v[152:153] op_sel_hi:[1,0]
	v_pk_mul_f32 v[4:5], v[4:5], v[152:153] op_sel_hi:[1,0]
	v_pk_mul_f32 v[2:3], v[2:3], v[152:153] op_sel_hi:[1,0]
	v_pk_mul_f32 v[0:1], v[0:1], v[152:153] op_sel_hi:[1,0]
	v_xor_b32_e32 v152, 0x80000000, v203
	v_sub_f32_e32 v66, v66, v229
	v_sub_f32_e32 v67, v67, v229
	v_sub_f32_e32 v68, v68, v229
	v_sub_f32_e32 v69, v69, v229
	v_sub_f32_e32 v70, v70, v229
	v_sub_f32_e32 v71, v71, v229
	v_sub_f32_e32 v72, v72, v229
	v_sub_f32_e32 v73, v73, v229
	v_sub_f32_e32 v74, v74, v229
	v_sub_f32_e32 v75, v75, v229
	v_sub_f32_e32 v76, v76, v229
	v_sub_f32_e32 v77, v77, v229
	v_sub_f32_e32 v78, v78, v229
	v_sub_f32_e32 v79, v79, v229
	v_sub_f32_e32 v48, v48, v229
	v_sub_f32_e32 v49, v49, v229
	v_sub_f32_e32 v50, v50, v229
	v_sub_f32_e32 v51, v51, v229
	v_sub_f32_e32 v52, v52, v229
	v_sub_f32_e32 v53, v53, v229
	v_sub_f32_e32 v54, v54, v229
	v_sub_f32_e32 v55, v55, v229
	v_sub_f32_e32 v56, v56, v229
	v_sub_f32_e32 v57, v57, v229
	v_sub_f32_e32 v58, v58, v229
	v_sub_f32_e32 v59, v59, v229
	v_sub_f32_e32 v60, v60, v229
	v_sub_f32_e32 v61, v61, v229
	v_sub_f32_e32 v62, v62, v229
	v_sub_f32_e32 v63, v63, v229
	v_cndmask_b32_sdwa v152, v113, v152, vcc dst_sel:DWORD dst_unused:UNUSED_PAD src0_sel:DWORD src1_sel:WORD_1
	v_mov_b32_e32 v154, 0
	v_mov_b32_e32 v153, 0
	s_branch .LBB0_451

.LBB0_451:
	v_exp_f32_e32 v64, v64
	v_exp_f32_e32 v65, v65
	v_exp_f32_e32 v66, v66
	s_waitcnt lgkmcnt(10)
	v_mfma_f32_32x32x16_bf16 v[80:95], v[212:215], v[120:123], v[80:95]
	ds_read_b128 v[208:211], v200 offset:32768
	v_exp_f32_e32 v67, v67
	v_exp_f32_e32 v68, v68
	v_exp_f32_e32 v69, v69
	s_waitcnt lgkmcnt(10)
	v_mfma_f32_32x32x16_bf16 v[96:111], v[216:219], v[124:127], v[96:111]
	ds_read_b128 v[212:215], v200 offset:36864
	v_exp_f32_e32 v70, v70
	v_exp_f32_e32 v71, v71
	v_cvt_pk_bf16_f32 v224, v64, v65
	v_cvt_pk_bf16_f32 v225, v66, v67
	s_waitcnt lgkmcnt(10)
	v_mfma_f32_32x32x16_bf16 v[80:95], v[220:223], v[124:127], v[80:95]
	ds_read_b128 v[216:219], v201 offset:32768
	v_cvt_pk_bf16_f32 v226, v68, v69
	v_cvt_pk_bf16_f32 v227, v70, v71
	v_exp_f32_e32 v72, v72
	v_exp_f32_e32 v73, v73
	s_waitcnt lgkmcnt(4)
	v_mfma_f32_32x32x16_bf16 v[32:47], v[174:177], v[224:227], v[32:47]
	ds_read_b128 v[220:223], v201 offset:36864
	v_exp_f32_e32 v74, v74
	v_exp_f32_e32 v75, v75
	v_exp_f32_e32 v76, v76
	s_waitcnt lgkmcnt(4)
	v_mfma_f32_32x32x16_bf16 v[16:31], v[204:207], v[224:227], v[16:31]
	v_exp_f32_e32 v77, v77
	v_exp_f32_e32 v78, v78
	v_exp_f32_e32 v79, v79
	v_mfma_f32_32x32x16_bf16 v[96:111], v[230:233], v[128:131], v[96:111]
	v_cvt_pk_bf16_f32 v224, v72, v73
	v_cvt_pk_bf16_f32 v225, v74, v75
	v_cvt_pk_bf16_f32 v226, v76, v77
	v_cvt_pk_bf16_f32 v227, v78, v79
	v_exp_f32_e32 v48, v48
	v_mfma_f32_32x32x16_bf16 v[80:95], v[234:237], v[128:131], v[80:95]
	ds_read_b128 v[230:233], v202 offset:32768
	v_exp_f32_e32 v49, v49
	v_exp_f32_e32 v50, v50
	v_exp_f32_e32 v51, v51
	s_waitcnt lgkmcnt(4)
	v_mfma_f32_32x32x16_bf16 v[32:47], v[208:211], v[224:227], v[32:47]
	ds_read_b128 v[234:237], v202 offset:36864
	v_exp_f32_e32 v52, v52
	v_exp_f32_e32 v53, v53
	v_exp_f32_e32 v54, v54
	s_waitcnt lgkmcnt(4)
	v_mfma_f32_32x32x16_bf16 v[16:31], v[212:215], v[224:227], v[16:31]
	v_exp_f32_e32 v55, v55
	v_cvt_pk_bf16_f32 v224, v48, v49
	v_cvt_pk_bf16_f32 v225, v50, v51
	v_cvt_pk_bf16_f32 v226, v52, v53
	v_cvt_pk_bf16_f32 v227, v54, v55
	v_mfma_f32_32x32x16_bf16 v[96:111], v[238:241], v[132:135], v[96:111]
	v_exp_f32_e32 v56, v56
	v_exp_f32_e32 v57, v57
	v_exp_f32_e32 v58, v58
	s_add_i32 s98, s73, 2
	s_cmp_ge_u32 s98, s70
	s_cbranch_scc1 .Lst_noK
	s_lshl_b32 s99, s68, 14
	v_add_u32_e32 v176, s99, v188
	s_waitcnt vmcnt(0)
	ds_write_b128 v176, v[144:147]
	s_and_saveexec_b64 s[100:101], s[6:7]
	v_add_u32_e32 v176, s99, v189
	ds_write_b128 v176, v[140:143]
	s_or_b64 exec, exec, s[100:101]
	s_nop 3
.Lst_noK:
	v_mfma_f32_32x32x16_bf16 v[80:95], v[242:245], v[132:135], v[80:95]
	v_exp_f32_e32 v59, v59
	v_exp_f32_e32 v60, v60
	v_exp_f32_e32 v61, v61
	s_and_b32 s99, s71, 0x2000
	v_add_u32_e32 v176, s99, v192
	v_add_u32_e32 v177, s99, v193
	s_waitcnt vmcnt(0)
	ds_write_b64 v176, v[148:149] offset:32768
	ds_write_b64 v177, v[150:151]
	s_waitcnt lgkmcnt(5)
	v_mfma_f32_32x32x16_bf16 v[32:47], v[216:219], v[224:227], v[32:47]
	v_exp_f32_e32 v62, v62
	v_exp_f32_e32 v63, v63
	v_pk_add_f32 v[64:65], v[48:49], v[64:65]
	s_add_i32 s99, s73, 3
	s_cmp_ge_u32 s99, s70
	s_cbranch_scc1 .Lst_noKL
	s_lshl_b64 s[100:101], s[14:15], 11
	v_lshl_add_u64 v[174:175], v[166:167], 0, s[100:101]
	global_load_dwordx4 v[144:147], v[174:175], off
	s_and_saveexec_b64 s[100:101], s[6:7]
	s_cbranch_execz .Lst_noR
	s_lshl_b64 s[78:79], s[14:15], 6
	v_lshl_add_u64 v[174:175], v[164:165], 0, s[78:79]
	global_load_dwordx4 v[140:143], v[174:175], off
.Lst_noR:
	s_or_b64 exec, exec, s[100:101]
	s_nop 3
.Lst_noKL:
	s_waitcnt lgkmcnt(4)
	v_mfma_f32_32x32x16_bf16 v[16:31], v[220:223], v[224:227], v[16:31]
	v_cvt_pk_bf16_f32 v224, v56, v57
	v_cvt_pk_bf16_f32 v225, v58, v59
	v_cvt_pk_bf16_f32 v226, v60, v61
	v_cvt_pk_bf16_f32 v227, v62, v63
	v_pk_add_f32 v[66:67], v[50:51], v[66:67]
	s_cmp_ge_u32 s98, s70
	s_cbranch_scc1 .Lst_noVL
	s_sub_i32 s100, s14, 64
	s_mov_b32 s101, s15
	v_lshl_add_u64 v[174:175], s[100:101], 1, v[168:169]
	global_load_dwordx4 v[148:151], v[174:175], off
.Lst_noVL:
	s_mov_b32 s98, 1
	v_mfma_f32_32x32x16_bf16 v[96:111], v[246:249], v[136:139], v[96:111]
	v_pk_add_f32 v[68:69], v[52:53], v[68:69]
	v_pk_add_f32 v[70:71], v[54:55], v[70:71]
	v_pk_add_f32 v[72:73], v[56:57], v[72:73]
	v_mfma_f32_32x32x16_bf16 v[80:95], v[250:253], v[136:139], v[80:95]
	v_pk_add_f32 v[74:75], v[58:59], v[74:75]
	v_pk_add_f32 v[76:77], v[60:61], v[76:77]
	v_pk_add_f32 v[78:79], v[62:63], v[78:79]
	s_waitcnt lgkmcnt(3)
	v_mfma_f32_32x32x16_bf16 v[32:47], v[230:233], v[224:227], v[32:47]
	v_pk_add_f32 v[0:1], v[64:65], v[0:1]
	v_pk_add_f32 v[2:3], v[66:67], v[2:3]
	v_pk_add_f32 v[4:5], v[68:69], v[4:5]
	s_waitcnt lgkmcnt(2)
	v_mfma_f32_32x32x16_bf16 v[16:31], v[234:237], v[224:227], v[16:31]
	v_cmp_neq_f32_e32 vcc, 0, v229
	v_pk_add_f32 v[6:7], v[70:71], v[6:7]
	v_pk_add_f32 v[8:9], v[72:73], v[8:9]
	v_pk_add_f32 v[10:11], v[74:75], v[10:11]
	v_pk_add_f32 v[12:13], v[76:77], v[12:13]
	v_pk_add_f32 v[14:15], v[78:79], v[14:15]
	s_cbranch_vccz .LBB0_453
	v_sub_f32_e32 v111, v111, v229
	v_sub_f32_e32 v110, v110, v229
	v_sub_f32_e32 v109, v109, v229
	v_sub_f32_e32 v108, v108, v229
	v_sub_f32_e32 v107, v107, v229
	v_sub_f32_e32 v106, v106, v229
	v_sub_f32_e32 v105, v105, v229
	v_sub_f32_e32 v104, v104, v229
	v_sub_f32_e32 v103, v103, v229
	v_sub_f32_e32 v102, v102, v229
	v_sub_f32_e32 v101, v101, v229
	v_sub_f32_e32 v100, v100, v229
	v_sub_f32_e32 v99, v99, v229
	v_sub_f32_e32 v98, v98, v229
	v_sub_f32_e32 v97, v97, v229
	v_sub_f32_e32 v96, v96, v229
	v_sub_f32_e32 v95, v95, v229
	v_sub_f32_e32 v94, v94, v229
	v_sub_f32_e32 v93, v93, v229
	v_sub_f32_e32 v92, v92, v229
	v_sub_f32_e32 v91, v91, v229
	v_sub_f32_e32 v90, v90, v229
	v_sub_f32_e32 v89, v89, v229
	v_sub_f32_e32 v88, v88, v229
	v_sub_f32_e32 v87, v87, v229
	v_sub_f32_e32 v86, v86, v229
	v_sub_f32_e32 v85, v85, v229
	v_sub_f32_e32 v84, v84, v229
	v_sub_f32_e32 v83, v83, v229
	v_sub_f32_e32 v82, v82, v229
	v_sub_f32_e32 v81, v81, v229
	v_sub_f32_e32 v80, v80, v229

.LBB0_456:
	s_or_b64 exec, exec, s[86:87]
	s_cmp_eq_u32 s98, 1
	s_cbranch_scc1 .LBB0_461
	s_add_i32 s69, s73, 2
	s_cmp_lt_u32 s69, s70
	s_cselect_b64 s[18:19], -1, 0
	s_cmp_ge_u32 s69, s70
	s_cbranch_scc0 .LBB0_463
	s_cmp_ge_u32 s74, s70
	s_cbranch_scc0 .LBB0_466

.Lmo_437:
	s_mov_b32 s98, 0
	s_and_b32 s68, s73, 1
	s_add_i32 s74, s73, 1
	s_lshl_b32 s69, s68, 13
	v_cmp_ge_i32_e32 vcc, s74, v197
	s_and_saveexec_b64 s[18:19], vcc
	s_xor_b64 s[86:87], exec, s[18:19]
	s_cbranch_execz .Lmo_445
	v_cmp_lt_i32_e32 vcc, s73, v197
	s_and_saveexec_b64 s[78:79], vcc
	s_cbranch_execz .Lmo_444
	v_max_f32_e32 v48, v97, v97
	v_max_f32_e32 v49, v96, v96
	v_max_f32_e32 v48, v49, v48
	v_max3_f32 v48, v48, v98, v99
	v_max3_f32 v48, v48, v100, v101
	v_max3_f32 v48, v48, v102, v103
	v_max3_f32 v48, v48, v104, v105
	v_max3_f32 v48, v48, v106, v107
	v_max3_f32 v48, v48, v108, v109
	v_max3_f32 v48, v48, v110, v111
	v_max3_f32 v48, v48, v80, v81
	v_max3_f32 v48, v48, v82, v83
	v_max3_f32 v48, v48, v84, v85
	v_max3_f32 v48, v48, v86, v87
	v_max3_f32 v48, v48, v88, v89
	v_max3_f32 v48, v48, v90, v91
	v_max3_f32 v48, v48, v92, v93
	s_cmp_eq_u32 s73, 0
	v_max3_f32 v48, v48, v94, v95
	s_cselect_b64 s[18:19], -1, 0
	v_cmp_lt_f32_e32 vcc, s29, v48
	s_or_b64 vcc, s[18:19], vcc
	s_cbranch_vccz .Lmo_443
	v_and_b32_e32 v50, 64, v172
	v_xor_b32_e32 v49, 32, v172
	v_add_u32_e32 v50, 64, v50
	v_cmp_lt_i32_e32 vcc, v49, v50
	v_mov_b32_e32 v155, 0
	s_nop 0
	v_cndmask_b32_e32 v49, v172, v49, vcc
	v_lshlrev_b32_e32 v49, 2, v49
	ds_bpermute_b32 v49, v49, v48
	v_max_f32_e32 v48, v48, v48
	s_waitcnt lgkmcnt(0)
	v_max_f32_e32 v49, v49, v49
	v_max_f32_e32 v49, v48, v49
	v_cmp_lt_f32_e32 vcc, s30, v49
	s_and_b64 s[18:19], s[18:19], vcc
	v_cmp_lt_f32_e32 vcc, s29, v49
	s_or_b64 vcc, vcc, s[18:19]
	v_mov_b32_e32 v48, 0
	s_and_saveexec_b64 s[18:19], vcc
	v_add_f32_e32 v48, v203, v49
	v_cvt_pk_bf16_f32 v48, v48, 0
	v_lshlrev_b32_e32 v49, 16, v48
	v_sub_f32_e32 v48, v49, v203
	v_mov_b32_e32 v203, v49
	s_or_b64 exec, exec, s[18:19]
	v_exp_f32_e64 v50, -v48
	s_mov_b64 vcc, s[8:9]
	v_sub_f32_e32 v111, v111, v48
	v_sub_f32_e32 v110, v110, v48
	v_sub_f32_e32 v109, v109, v48
	v_sub_f32_e32 v108, v108, v48
	v_sub_f32_e32 v107, v107, v48
	v_sub_f32_e32 v106, v106, v48
	v_sub_f32_e32 v105, v105, v48
	v_sub_f32_e32 v104, v104, v48
	v_sub_f32_e32 v103, v103, v48
	v_sub_f32_e32 v102, v102, v48
	v_sub_f32_e32 v101, v101, v48
	v_sub_f32_e32 v100, v100, v48
	v_sub_f32_e32 v99, v99, v48
	v_sub_f32_e32 v98, v98, v48
	v_sub_f32_e32 v97, v97, v48
	v_sub_f32_e32 v96, v96, v48
	v_sub_f32_e32 v95, v95, v48
	v_sub_f32_e32 v94, v94, v48
	v_sub_f32_e32 v93, v93, v48
	v_sub_f32_e32 v92, v92, v48
	v_sub_f32_e32 v91, v91, v48
	v_sub_f32_e32 v90, v90, v48
	v_sub_f32_e32 v89, v89, v48
	v_sub_f32_e32 v88, v88, v48
	v_sub_f32_e32 v87, v87, v48
	v_sub_f32_e32 v86, v86, v48
	v_sub_f32_e32 v85, v85, v48
	v_sub_f32_e32 v84, v84, v48
	v_sub_f32_e32 v83, v83, v48
	v_sub_f32_e32 v82, v82, v48
	v_sub_f32_e32 v81, v81, v48
	v_sub_f32_e32 v80, v80, v48
	v_xor_b32_e32 v48, 0x80000000, v203
	v_pk_mul_f32 v[46:47], v[46:47], v[50:51] op_sel_hi:[1,0]
	v_pk_mul_f32 v[44:45], v[44:45], v[50:51] op_sel_hi:[1,0]
	v_pk_mul_f32 v[42:43], v[42:43], v[50:51] op_sel_hi:[1,0]
	v_pk_mul_f32 v[40:41], v[40:41], v[50:51] op_sel_hi:[1,0]
	v_pk_mul_f32 v[38:39], v[38:39], v[50:51] op_sel_hi:[1,0]
	v_pk_mul_f32 v[36:37], v[36:37], v[50:51] op_sel_hi:[1,0]
	v_pk_mul_f32 v[34:35], v[34:35], v[50:51] op_sel_hi:[1,0]
	v_pk_mul_f32 v[32:33], v[32:33], v[50:51] op_sel_hi:[1,0]
	v_pk_mul_f32 v[30:31], v[30:31], v[50:51] op_sel_hi:[1,0]
	v_pk_mul_f32 v[28:29], v[28:29], v[50:51] op_sel_hi:[1,0]
	v_pk_mul_f32 v[26:27], v[26:27], v[50:51] op_sel_hi:[1,0]
	v_pk_mul_f32 v[24:25], v[24:25], v[50:51] op_sel_hi:[1,0]
	v_pk_mul_f32 v[22:23], v[22:23], v[50:51] op_sel_hi:[1,0]
	v_pk_mul_f32 v[20:21], v[20:21], v[50:51] op_sel_hi:[1,0]
	v_pk_mul_f32 v[18:19], v[18:19], v[50:51] op_sel_hi:[1,0]
	v_pk_mul_f32 v[16:17], v[16:17], v[50:51] op_sel_hi:[1,0]
	v_pk_mul_f32 v[14:15], v[14:15], v[50:51] op_sel_hi:[1,0]
	v_pk_mul_f32 v[12:13], v[12:13], v[50:51] op_sel_hi:[1,0]
	v_pk_mul_f32 v[10:11], v[10:11], v[50:51] op_sel_hi:[1,0]
	v_pk_mul_f32 v[8:9], v[8:9], v[50:51] op_sel_hi:[1,0]
	v_pk_mul_f32 v[6:7], v[6:7], v[50:51] op_sel_hi:[1,0]
	v_pk_mul_f32 v[4:5], v[4:5], v[50:51] op_sel_hi:[1,0]
	v_pk_mul_f32 v[2:3], v[2:3], v[50:51] op_sel_hi:[1,0]
	v_pk_mul_f32 v[0:1], v[0:1], v[50:51] op_sel_hi:[1,0]
	v_cndmask_b32_sdwa v152, v113, v48, vcc dst_sel:DWORD dst_unused:UNUSED_PAD src0_sel:DWORD src1_sel:WORD_1
	v_mov_b32_e32 v154, 0
	v_mov_b32_e32 v153, 0
.Lmo_443:
	s_nop 0
	v_add_u32_e32 v69, s69, v199
	ds_read_b128 v[64:67], v69 offset:32768
	v_exp_f32_e32 v108, v108
	v_exp_f32_e32 v92, v92
	v_exp_f32_e32 v109, v109
	v_exp_f32_e32 v93, v93
	v_exp_f32_e32 v110, v110
	v_exp_f32_e32 v94, v94
	v_exp_f32_e32 v111, v111
	v_exp_f32_e32 v95, v95
	v_exp_f32_e32 v96, v96
	v_exp_f32_e32 v97, v97
	v_exp_f32_e32 v98, v98
	v_exp_f32_e32 v99, v99
	v_exp_f32_e32 v100, v100
	v_exp_f32_e32 v101, v101
	v_exp_f32_e32 v102, v102
	v_exp_f32_e32 v103, v103
	v_pk_add_f32 v[60:61], v[92:93], v[108:109]
	v_pk_add_f32 v[62:63], v[94:95], v[110:111]
	v_pk_add_f32 v[12:13], v[60:61], v[12:13]
	v_pk_add_f32 v[14:15], v[62:63], v[14:15]
	v_cvt_pk_bf16_f32 v60, v96, v97
	v_cvt_pk_bf16_f32 v61, v98, v99
	v_cvt_pk_bf16_f32 v62, v100, v101
	v_cvt_pk_bf16_f32 v63, v102, v103
	v_exp_f32_e32 v104, v104
	v_exp_f32_e32 v88, v88
	s_waitcnt lgkmcnt(0)
	v_mfma_f32_32x32x16_bf16 v[32:47], v[64:67], v[60:63], v[32:47]
	ds_read_b128 v[64:67], v69 offset:36864
	v_exp_f32_e32 v105, v105
	v_exp_f32_e32 v89, v89
	v_exp_f32_e32 v106, v106
	v_exp_f32_e32 v90, v90
	v_exp_f32_e32 v107, v107
	v_exp_f32_e32 v91, v91
	s_waitcnt lgkmcnt(0)
	v_mfma_f32_32x32x16_bf16 v[16:31], v[64:67], v[60:63], v[16:31]
	v_add_u32_e32 v64, s69, v200
	ds_read_b128 v[60:63], v64 offset:32768
	v_add_f32_e64 v56, v88, v104
	v_add_f32_e64 v57, v89, v105
	v_add_f32_e64 v58, v90, v106
	v_add_f32_e64 v59, v91, v107
	v_pk_add_f32 v[8:9], v[56:57], v[8:9]
	v_pk_add_f32 v[10:11], v[58:59], v[10:11]
	v_cvt_pk_bf16_f32 v56, v104, v105
	v_cvt_pk_bf16_f32 v57, v106, v107
	v_cvt_pk_bf16_f32 v58, v108, v109
	v_cvt_pk_bf16_f32 v59, v110, v111
	v_exp_f32_e32 v84, v84
	v_exp_f32_e32 v85, v85
	s_waitcnt lgkmcnt(0)
	v_mfma_f32_32x32x16_bf16 v[32:47], v[60:63], v[56:59], v[32:47]
	ds_read_b128 v[60:63], v64 offset:36864
	v_exp_f32_e32 v86, v86
	v_exp_f32_e32 v87, v87
	v_exp_f32_e32 v80, v80
	v_exp_f32_e32 v81, v81
	v_exp_f32_e32 v82, v82
	v_exp_f32_e32 v83, v83
	s_waitcnt lgkmcnt(0)
	v_mfma_f32_32x32x16_bf16 v[16:31], v[60:63], v[56:59], v[16:31]
	v_add_u32_e32 v60, s69, v201
	ds_read_b128 v[56:59], v60 offset:32768
	v_add_f32_e64 v52, v84, v100
	v_add_f32_e64 v53, v85, v101
	v_add_f32_e64 v54, v86, v102
	v_add_f32_e64 v55, v87, v103
	v_pk_add_f32 v[4:5], v[52:53], v[4:5]
	v_pk_add_f32 v[6:7], v[54:55], v[6:7]
	v_cvt_pk_bf16_f32 v52, v80, v81
	v_cvt_pk_bf16_f32 v53, v82, v83
	v_cvt_pk_bf16_f32 v54, v84, v85
	v_cvt_pk_bf16_f32 v55, v86, v87
	v_pk_add_f32 v[48:49], v[80:81], v[96:97]
	v_pk_add_f32 v[50:51], v[82:83], v[98:99]
	s_waitcnt lgkmcnt(0)
	v_mfma_f32_32x32x16_bf16 v[32:47], v[56:59], v[52:55], v[32:47]
	ds_read_b128 v[56:59], v60 offset:36864
	v_add_f32_e64 v2, v50, v2
	v_add_f32_e64 v3, v51, v3
	v_add_f32_e64 v0, v48, v0
	v_add_f32_e64 v1, v49, v1
	v_cvt_pk_bf16_f32 v48, v88, v89
	v_cvt_pk_bf16_f32 v49, v90, v91
	v_cvt_pk_bf16_f32 v50, v92, v93
	v_cvt_pk_bf16_f32 v51, v94, v95
	s_waitcnt lgkmcnt(0)
	v_mfma_f32_32x32x16_bf16 v[16:31], v[56:59], v[52:55], v[16:31]
	v_add_u32_e32 v56, s69, v202
	ds_read_b128 v[52:55], v56 offset:32768
	s_waitcnt lgkmcnt(0)
	v_mfma_f32_32x32x16_bf16 v[32:47], v[52:55], v[48:51], v[32:47]
	ds_read_b128 v[52:55], v56 offset:36864
	s_waitcnt lgkmcnt(0)
	v_mfma_f32_32x32x16_bf16 v[16:31], v[52:55], v[48:51], v[16:31]

.Lmo_445:
	s_andn2_saveexec_b64 s[86:87], s[86:87]
	s_cbranch_execz .Lmo_456
	ds_read_b128 v[174:177], v186 offset:0
	ds_read_b128 v[204:207], v186 offset:8192
	v_mfma_f32_32x32x16_bf16 v[48:63], v[112:115], v[152:155], 0
	ds_read_b128 v[208:211], v184 offset:0
	ds_read_b128 v[212:215], v184 offset:8192
	ds_read_b128 v[216:219], v183 offset:0
	ds_read_b128 v[220:223], v183 offset:8192
	ds_read_b128 v[230:233], v191 offset:0
	ds_read_b128 v[234:237], v191 offset:8192
	ds_read_b128 v[238:241], v190 offset:0
	ds_read_b128 v[242:245], v190 offset:8192
	ds_read_b128 v[246:249], v187 offset:0
	ds_read_b128 v[250:253], v187 offset:8192
	s_cmp_eq_u32 s73, 0
	s_cselect_b64 s[78:79], -1, 0
	v_max_f32_e32 v224, v97, v97
	v_max_f32_e32 v225, v96, v96
	v_max_f32_e32 v224, v225, v224
	v_max3_f32 v224, v224, v98, v99
	v_max3_f32 v224, v224, v100, v101
	s_waitcnt lgkmcnt(11)
	v_mfma_f32_32x32x16_bf16 v[64:79], v[174:177], v[116:119], v[48:63]
	v_max3_f32 v224, v224, v102, v103
	v_max3_f32 v224, v224, v104, v105
	v_max3_f32 v224, v224, v106, v107
	v_max3_f32 v224, v224, v108, v109
	v_max3_f32 v224, v224, v110, v111
	v_max3_f32 v224, v224, v80, v81
	s_waitcnt lgkmcnt(10)
	v_mfma_f32_32x32x16_bf16 v[48:63], v[204:207], v[116:119], v[48:63]
	ds_read_b128 v[174:177], v199 offset:40960
	v_max3_f32 v224, v224, v82, v83
	v_max3_f32 v224, v224, v84, v85
	v_max3_f32 v224, v224, v86, v87
	v_max3_f32 v224, v224, v88, v89
	v_max3_f32 v224, v224, v90, v91
	v_max3_f32 v224, v224, v92, v93
	v_max3_f32 v229, v224, v94, v95
	v_cmp_lt_f32_e32 vcc, s29, v229
	s_or_b64 vcc, s[78:79], vcc
	s_waitcnt lgkmcnt(10)
	v_mfma_f32_32x32x16_bf16 v[64:79], v[208:211], v[120:123], v[64:79]
	ds_read_b128 v[204:207], v199 offset:45056
	s_cbranch_vccz .Lmo_450
	v_and_b32_e32 v153, 64, v172
	v_xor_b32_e32 v152, 32, v172
	v_add_u32_e32 v153, 64, v153
	v_cmp_lt_i32_e32 vcc, v152, v153
	v_max_f32_e32 v153, v229, v229
	v_mov_b32_e32 v155, 0
	v_cndmask_b32_e32 v152, v172, v152, vcc
	v_lshlrev_b32_e32 v152, 2, v152
	ds_bpermute_b32 v152, v152, v229
	v_mov_b32_e32 v229, 0
	s_waitcnt lgkmcnt(0)
	v_max_f32_e32 v152, v152, v152
	v_max_f32_e32 v152, v153, v152
	v_cmp_lt_f32_e32 vcc, s30, v152
	s_and_b64 s[18:19], s[78:79], vcc
	v_cmp_lt_f32_e32 vcc, s29, v152
	s_or_b64 s[78:79], vcc, s[18:19]
	s_and_saveexec_b64 s[18:19], s[78:79]
	v_add_f32_e32 v152, v203, v152
	v_cvt_pk_bf16_f32 v152, v152, 0
	v_lshlrev_b32_e32 v152, 16, v152
	v_sub_f32_e32 v229, v152, v203
	v_mov_b32_e32 v203, v152
	s_or_b64 exec, exec, s[18:19]
	v_exp_f32_e64 v152, -v229
	s_mov_b64 vcc, s[8:9]
	v_sub_f32_e32 v96, v96, v229
	v_sub_f32_e32 v97, v97, v229
	v_pk_mul_f32 v[46:47], v[46:47], v[152:153] op_sel_hi:[1,0]
	v_pk_mul_f32 v[44:45], v[44:45], v[152:153] op_sel_hi:[1,0]
	v_pk_mul_f32 v[42:43], v[42:43], v[152:153] op_sel_hi:[1,0]
	v_pk_mul_f32 v[40:41], v[40:41], v[152:153] op_sel_hi:[1,0]
	v_pk_mul_f32 v[38:39], v[38:39], v[152:153] op_sel_hi:[1,0]
	v_pk_mul_f32 v[36:37], v[36:37], v[152:153] op_sel_hi:[1,0]
	v_pk_mul_f32 v[34:35], v[34:35], v[152:153] op_sel_hi:[1,0]
	v_pk_mul_f32 v[32:33], v[32:33], v[152:153] op_sel_hi:[1,0]
	v_pk_mul_f32 v[30:31], v[30:31], v[152:153] op_sel_hi:[1,0]
	v_pk_mul_f32 v[28:29], v[28:29], v[152:153] op_sel_hi:[1,0]
	v_pk_mul_f32 v[26:27], v[26:27], v[152:153] op_sel_hi:[1,0]
	v_pk_mul_f32 v[24:25], v[24:25], v[152:153] op_sel_hi:[1,0]
	v_pk_mul_f32 v[22:23], v[22:23], v[152:153] op_sel_hi:[1,0]
	v_pk_mul_f32 v[20:21], v[20:21], v[152:153] op_sel_hi:[1,0]
	v_pk_mul_f32 v[18:19], v[18:19], v[152:153] op_sel_hi:[1,0]
	v_pk_mul_f32 v[16:17], v[16:17], v[152:153] op_sel_hi:[1,0]
	v_pk_mul_f32 v[14:15], v[14:15], v[152:153] op_sel_hi:[1,0]
	v_pk_mul_f32 v[12:13], v[12:13], v[152:153] op_sel_hi:[1,0]
	v_pk_mul_f32 v[10:11], v[10:11], v[152:153] op_sel_hi:[1,0]
	v_pk_mul_f32 v[8:9], v[8:9], v[152:153] op_sel_hi:[1,0]
	v_pk_mul_f32 v[6:7], v[6:7], v[152:153] op_sel_hi:[1,0]
	v_pk_mul_f32 v[4:5], v[4:5], v[152:153] op_sel_hi:[1,0]
	v_pk_mul_f32 v[2:3], v[2:3], v[152:153] op_sel_hi:[1,0]
	v_pk_mul_f32 v[0:1], v[0:1], v[152:153] op_sel_hi:[1,0]
	v_xor_b32_e32 v152, 0x80000000, v203
	v_sub_f32_e32 v98, v98, v229
	v_sub_f32_e32 v99, v99, v229
	v_sub_f32_e32 v100, v100, v229
	v_sub_f32_e32 v101, v101, v229
	v_sub_f32_e32 v102, v102, v229
	v_sub_f32_e32 v103, v103, v229
	v_sub_f32_e32 v104, v104, v229
	v_sub_f32_e32 v105, v105, v229
	v_sub_f32_e32 v106, v106, v229
	v_sub_f32_e32 v107, v107, v229
	v_sub_f32_e32 v108, v108, v229
	v_sub_f32_e32 v109, v109, v229
	v_sub_f32_e32 v110, v110, v229
	v_sub_f32_e32 v111, v111, v229
	v_sub_f32_e32 v80, v80, v229
	v_sub_f32_e32 v81, v81, v229
	v_sub_f32_e32 v82, v82, v229
	v_sub_f32_e32 v83, v83, v229
	v_sub_f32_e32 v84, v84, v229
	v_sub_f32_e32 v85, v85, v229
	v_sub_f32_e32 v86, v86, v229
	v_sub_f32_e32 v87, v87, v229
	v_sub_f32_e32 v88, v88, v229
	v_sub_f32_e32 v89, v89, v229
	v_sub_f32_e32 v90, v90, v229
	v_sub_f32_e32 v91, v91, v229
	v_sub_f32_e32 v92, v92, v229
	v_sub_f32_e32 v93, v93, v229
	v_sub_f32_e32 v94, v94, v229
	v_sub_f32_e32 v95, v95, v229
	v_cndmask_b32_sdwa v152, v113, v152, vcc dst_sel:DWORD dst_unused:UNUSED_PAD src0_sel:DWORD src1_sel:WORD_1
	v_mov_b32_e32 v154, 0
	v_mov_b32_e32 v153, 0
	s_branch .Lmo_451

.Lmo_451:
	v_exp_f32_e32 v96, v96
	v_exp_f32_e32 v97, v97
	v_exp_f32_e32 v98, v98
	s_waitcnt lgkmcnt(10)
	v_mfma_f32_32x32x16_bf16 v[48:63], v[212:215], v[120:123], v[48:63]
	ds_read_b128 v[208:211], v200 offset:40960
	v_exp_f32_e32 v99, v99
	v_exp_f32_e32 v100, v100
	v_exp_f32_e32 v101, v101
	s_waitcnt lgkmcnt(10)
	v_mfma_f32_32x32x16_bf16 v[64:79], v[216:219], v[124:127], v[64:79]
	ds_read_b128 v[212:215], v200 offset:45056
	v_exp_f32_e32 v102, v102
	v_exp_f32_e32 v103, v103
	v_cvt_pk_bf16_f32 v224, v96, v97
	v_cvt_pk_bf16_f32 v225, v98, v99
	s_waitcnt lgkmcnt(10)
	v_mfma_f32_32x32x16_bf16 v[48:63], v[220:223], v[124:127], v[48:63]
	ds_read_b128 v[216:219], v201 offset:40960
	v_cvt_pk_bf16_f32 v226, v100, v101
	v_cvt_pk_bf16_f32 v227, v102, v103
	v_exp_f32_e32 v104, v104
	v_exp_f32_e32 v105, v105
	s_waitcnt lgkmcnt(4)
	v_mfma_f32_32x32x16_bf16 v[32:47], v[174:177], v[224:227], v[32:47]
	ds_read_b128 v[220:223], v201 offset:45056
	v_exp_f32_e32 v106, v106
	v_exp_f32_e32 v107, v107
	v_exp_f32_e32 v108, v108
	s_waitcnt lgkmcnt(4)
	v_mfma_f32_32x32x16_bf16 v[16:31], v[204:207], v[224:227], v[16:31]
	v_exp_f32_e32 v109, v109
	v_exp_f32_e32 v110, v110
	v_exp_f32_e32 v111, v111
	v_mfma_f32_32x32x16_bf16 v[64:79], v[230:233], v[128:131], v[64:79]
	v_cvt_pk_bf16_f32 v224, v104, v105
	v_cvt_pk_bf16_f32 v225, v106, v107
	v_cvt_pk_bf16_f32 v226, v108, v109
	v_cvt_pk_bf16_f32 v227, v110, v111
	v_exp_f32_e32 v80, v80
	v_mfma_f32_32x32x16_bf16 v[48:63], v[234:237], v[128:131], v[48:63]
	ds_read_b128 v[230:233], v202 offset:40960
	v_exp_f32_e32 v81, v81
	v_exp_f32_e32 v82, v82
	v_exp_f32_e32 v83, v83
	s_waitcnt lgkmcnt(4)
	v_mfma_f32_32x32x16_bf16 v[32:47], v[208:211], v[224:227], v[32:47]
	ds_read_b128 v[234:237], v202 offset:45056
	v_exp_f32_e32 v84, v84
	v_exp_f32_e32 v85, v85
	v_exp_f32_e32 v86, v86
	s_waitcnt lgkmcnt(4)
	v_mfma_f32_32x32x16_bf16 v[16:31], v[212:215], v[224:227], v[16:31]
	v_exp_f32_e32 v87, v87
	v_cvt_pk_bf16_f32 v224, v80, v81
	v_cvt_pk_bf16_f32 v225, v82, v83
	v_cvt_pk_bf16_f32 v226, v84, v85
	v_cvt_pk_bf16_f32 v227, v86, v87
	v_mfma_f32_32x32x16_bf16 v[64:79], v[238:241], v[132:135], v[64:79]
	v_exp_f32_e32 v88, v88
	v_exp_f32_e32 v89, v89
	v_exp_f32_e32 v90, v90
	s_add_i32 s98, s73, 2
	s_cmp_ge_u32 s98, s70
	s_cbranch_scc1 .Lsto_noK
	s_lshl_b32 s99, s68, 14
	v_add_u32_e32 v176, s99, v188
	s_waitcnt vmcnt(0)
	ds_write_b128 v176, v[144:147]
	s_and_saveexec_b64 s[100:101], s[6:7]
	v_add_u32_e32 v176, s99, v189
	ds_write_b128 v176, v[140:143]
	s_or_b64 exec, exec, s[100:101]
	s_nop 3
.Lsto_noK:
	v_mfma_f32_32x32x16_bf16 v[48:63], v[242:245], v[132:135], v[48:63]
	v_exp_f32_e32 v91, v91
	v_exp_f32_e32 v92, v92
	v_exp_f32_e32 v93, v93
	s_and_b32 s99, s71, 0x2000
	v_add_u32_e32 v176, s99, v192
	v_add_u32_e32 v177, s99, v193
	s_waitcnt vmcnt(0)
	ds_write_b64 v176, v[148:149] offset:32768
	ds_write_b64 v177, v[150:151]
	s_waitcnt lgkmcnt(5)
	v_mfma_f32_32x32x16_bf16 v[32:47], v[216:219], v[224:227], v[32:47]
	v_exp_f32_e32 v94, v94
	v_exp_f32_e32 v95, v95
	v_pk_add_f32 v[96:97], v[80:81], v[96:97]
	s_add_i32 s99, s73, 3
	s_cmp_ge_u32 s99, s70
	s_cbranch_scc1 .Lsto_noKL
	s_lshl_b64 s[100:101], s[14:15], 11
	v_lshl_add_u64 v[174:175], v[166:167], 0, s[100:101]
	global_load_dwordx4 v[144:147], v[174:175], off
	s_and_saveexec_b64 s[100:101], s[6:7]
	s_cbranch_execz .Lsto_noR
	s_lshl_b64 s[78:79], s[14:15], 6
	v_lshl_add_u64 v[174:175], v[164:165], 0, s[78:79]
	global_load_dwordx4 v[140:143], v[174:175], off

.Lsto_noKL:
	s_waitcnt lgkmcnt(4)
	v_mfma_f32_32x32x16_bf16 v[16:31], v[220:223], v[224:227], v[16:31]
	v_cvt_pk_bf16_f32 v224, v88, v89
	v_cvt_pk_bf16_f32 v225, v90, v91
	v_cvt_pk_bf16_f32 v226, v92, v93
	v_cvt_pk_bf16_f32 v227, v94, v95
	v_pk_add_f32 v[98:99], v[82:83], v[98:99]
	s_cmp_ge_u32 s98, s70
	s_cbranch_scc1 .Lsto_noVL
	s_sub_i32 s100, s14, 64
	s_mov_b32 s101, s15
	v_lshl_add_u64 v[174:175], s[100:101], 1, v[168:169]
	global_load_dwordx4 v[148:151], v[174:175], off
.Lsto_noVL:
	s_mov_b32 s98, 1
	v_mfma_f32_32x32x16_bf16 v[64:79], v[246:249], v[136:139], v[64:79]
	v_pk_add_f32 v[100:101], v[84:85], v[100:101]
	v_pk_add_f32 v[102:103], v[86:87], v[102:103]
	v_pk_add_f32 v[104:105], v[88:89], v[104:105]
	v_mfma_f32_32x32x16_bf16 v[48:63], v[250:253], v[136:139], v[48:63]
	v_pk_add_f32 v[106:107], v[90:91], v[106:107]
	v_pk_add_f32 v[108:109], v[92:93], v[108:109]
	v_pk_add_f32 v[110:111], v[94:95], v[110:111]
	s_waitcnt lgkmcnt(3)
	v_mfma_f32_32x32x16_bf16 v[32:47], v[230:233], v[224:227], v[32:47]
	v_pk_add_f32 v[0:1], v[96:97], v[0:1]
	v_pk_add_f32 v[2:3], v[98:99], v[2:3]
	v_pk_add_f32 v[4:5], v[100:101], v[4:5]
	s_waitcnt lgkmcnt(2)
	v_mfma_f32_32x32x16_bf16 v[16:31], v[234:237], v[224:227], v[16:31]
	v_cmp_neq_f32_e32 vcc, 0, v229
	v_pk_add_f32 v[6:7], v[102:103], v[6:7]
	v_pk_add_f32 v[8:9], v[104:105], v[8:9]
	v_pk_add_f32 v[10:11], v[106:107], v[10:11]
	v_pk_add_f32 v[12:13], v[108:109], v[12:13]
	v_pk_add_f32 v[14:15], v[110:111], v[14:15]
	s_cbranch_vccz .Lmo_453
	v_sub_f32_e32 v79, v79, v229
	v_sub_f32_e32 v78, v78, v229
	v_sub_f32_e32 v77, v77, v229
	v_sub_f32_e32 v76, v76, v229
	v_sub_f32_e32 v75, v75, v229
	v_sub_f32_e32 v74, v74, v229
	v_sub_f32_e32 v73, v73, v229
	v_sub_f32_e32 v72, v72, v229
	v_sub_f32_e32 v71, v71, v229
	v_sub_f32_e32 v70, v70, v229
	v_sub_f32_e32 v69, v69, v229
	v_sub_f32_e32 v68, v68, v229
	v_sub_f32_e32 v67, v67, v229
	v_sub_f32_e32 v66, v66, v229
	v_sub_f32_e32 v65, v65, v229
	v_sub_f32_e32 v64, v64, v229
	v_sub_f32_e32 v63, v63, v229
	v_sub_f32_e32 v62, v62, v229
	v_sub_f32_e32 v61, v61, v229
	v_sub_f32_e32 v60, v60, v229
	v_sub_f32_e32 v59, v59, v229
	v_sub_f32_e32 v58, v58, v229
	v_sub_f32_e32 v57, v57, v229
	v_sub_f32_e32 v56, v56, v229
	v_sub_f32_e32 v55, v55, v229
	v_sub_f32_e32 v54, v54, v229
	v_sub_f32_e32 v53, v53, v229
	v_sub_f32_e32 v52, v52, v229
	v_sub_f32_e32 v51, v51, v229
	v_sub_f32_e32 v50, v50, v229
	v_sub_f32_e32 v49, v49, v229
	v_sub_f32_e32 v48, v48, v229

.LBB0_470:
	v_sub_u32_e32 v186, v186, v194
	v_sub_u32_e32 v184, v184, v194
	v_sub_u32_e32 v183, v183, v194
	v_sub_u32_e32 v191, v191, v194
	v_sub_u32_e32 v190, v190, v194
	v_sub_u32_e32 v187, v187, v194
	s_setprio 0
	v_add_f32_e32 v0, 0, v0
	v_add_f32_e32 v0, v1, v0
	v_add_f32_e32 v0, v2, v0
	v_add_f32_e32 v0, v3, v0
	v_add_f32_e32 v0, v4, v0
	v_add_f32_e32 v0, v5, v0
	v_add_f32_e32 v0, v6, v0
	v_add_f32_e32 v0, v7, v0
	v_add_f32_e32 v0, v8, v0
	v_add_f32_e32 v0, v9, v0
	v_add_f32_e32 v0, v10, v0
	v_add_f32_e32 v0, v11, v0
	v_and_b32_e32 v2, 64, v172
	v_add_f32_e32 v0, v12, v0
	v_xor_b32_e32 v1, 32, v172
	v_add_u32_e32 v2, 64, v2
	v_add_f32_e32 v0, v13, v0
	v_cmp_lt_i32_e32 vcc, v1, v2
	v_add_f32_e32 v0, v14, v0
	v_add_f32_e32 v0, v15, v0
	v_cndmask_b32_e32 v1, v172, v1, vcc
	v_lshlrev_b32_e32 v1, 2, v1
	ds_bpermute_b32 v1, v1, v0
	s_add_i32 s14, s4, s31
	v_ashrrev_i32_e32 v161, 31, v160
	v_lshl_add_u64 v[4:5], v[160:161], 0, s[14:15]
	s_lshl_b32 s14, s5, 1
	v_lshrrev_b32_e32 v55, 3, v185
	s_add_u32 s4, s60, s14
	v_lshlrev_b32_e32 v2, 4, v185
	s_waitcnt lgkmcnt(0)
	v_add_f32_e32 v10, v0, v1
	v_or_b32_e32 v0, v4, v55
	v_mov_b32_e32 v1, v5
	s_addc_u32 s5, s61, 0
	v_and_b32_e32 v112, 0x70, v2
	v_lshl_add_u64 v[2:3], s[4:5], 0, v[112:113]
	v_lshlrev_b64 v[52:53], 11, v[0:1]
	v_lshl_add_u64 v[0:1], v[2:3], 0, v[52:53]
	global_load_dwordx4 v[6:9], v[0:1], off
	v_div_scale_f32 v2, s[4:5], v10, v10, 1.0
	v_rcp_f32_e32 v3, v2
	v_lshlrev_b32_e32 v56, 13, v182
	v_lshlrev_b32_e32 v14, 8, v185
	s_movk_i32 s4, 0x1f00
	v_fma_f32 v11, -v2, v3, 1.0
	v_fmac_f32_e32 v3, v11, v3
	v_div_scale_f32 v11, vcc, 1.0, v10, 1.0
	v_mul_f32_e32 v12, v11, v3
	v_fma_f32 v13, -v2, v12, v11
	v_fmac_f32_e32 v12, v13, v3
	v_fma_f32 v2, -v2, v12, v11
	v_div_fmas_f32 v2, v2, v3, v12
	v_div_fixup_f32 v54, v2, v10, 1.0
	v_add_co_u32_e32 v2, vcc, s83, v0
	v_and_or_b32 v57, v14, s4, v56
	s_nop 0
	v_addc_co_u32_e32 v3, vcc, 0, v1, vcc
	global_load_dwordx4 v[10:13], v[2:3], off
	v_add_co_u32_e32 v2, vcc, s81, v0
	v_pk_mul_f32 v[32:33], v[32:33], v[54:55] op_sel_hi:[1,0]
	s_nop 0
	v_addc_co_u32_e32 v3, vcc, 0, v1, vcc
	v_add_co_u32_e32 v0, vcc, s3, v0
	v_pk_mul_f32 v[34:35], v[34:35], v[54:55] op_sel_hi:[1,0]
	s_nop 0
	v_addc_co_u32_e32 v1, vcc, 0, v1, vcc
	global_load_dwordx4 v[48:51], v[2:3], off
	s_nop 0
	global_load_dwordx4 v[0:3], v[0:1], off
	v_or_b32_e32 v14, v57, v186
	ds_write_b128 v14, v[32:35]
	v_pk_mul_f32 v[32:33], v[36:37], v[54:55] op_sel_hi:[1,0]
	v_pk_mul_f32 v[34:35], v[38:39], v[54:55] op_sel_hi:[1,0]
	v_or_b32_e32 v14, v57, v184
	ds_write_b128 v14, v[32:35]
	v_pk_mul_f32 v[32:33], v[40:41], v[54:55] op_sel_hi:[1,0]
	v_pk_mul_f32 v[34:35], v[42:43], v[54:55] op_sel_hi:[1,0]
	v_or_b32_e32 v14, v57, v183
	ds_write_b128 v14, v[32:35]
	v_pk_mul_f32 v[32:33], v[44:45], v[54:55] op_sel_hi:[1,0]
	v_pk_mul_f32 v[34:35], v[46:47], v[54:55] op_sel_hi:[1,0]
	v_or_b32_e32 v14, v57, v191
	ds_write_b128 v14, v[32:35]
	v_pk_mul_f32 v[14:15], v[16:17], v[54:55] op_sel_hi:[1,0]
	v_pk_mul_f32 v[16:17], v[18:19], v[54:55] op_sel_hi:[1,0]
	v_or_b32_e32 v18, v57, v190
	ds_write_b128 v18, v[14:17]
	v_pk_mul_f32 v[14:15], v[20:21], v[54:55] op_sel_hi:[1,0]
	v_pk_mul_f32 v[16:17], v[22:23], v[54:55] op_sel_hi:[1,0]
	v_or_b32_e32 v18, v57, v187
	ds_write_b128 v18, v[14:17]
	v_bitop3_b32 v18, v171, v159, 12 bitop3:0x36
	v_pk_mul_f32 v[14:15], v[24:25], v[54:55] op_sel_hi:[1,0]
	v_pk_mul_f32 v[16:17], v[26:27], v[54:55] op_sel_hi:[1,0]
	v_lshl_or_b32 v18, v18, 4, v57
	ds_write_b128 v18, v[14:17]
	v_bitop3_b32 v18, v171, v159, 14 bitop3:0x36
	v_pk_mul_f32 v[14:15], v[28:29], v[54:55] op_sel_hi:[1,0]
	v_pk_mul_f32 v[16:17], v[30:31], v[54:55] op_sel_hi:[1,0]
	v_lshl_or_b32 v18, v18, 4, v57
	v_lshlrev_b32_e32 v24, 1, v163
	ds_write_b128 v18, v[14:17]
	v_xor_b32_e32 v14, v55, v24
	v_lshl_or_b32 v18, v55, 8, v56
	v_lshlrev_b32_e32 v26, 4, v14
	v_or_b32_e32 v14, v18, v26
	ds_read_b128 v[14:17], v14
	v_bitop3_b32 v19, v24, v55, 1 bitop3:0x36
	v_lshlrev_b32_e32 v27, 4, v19
	v_or_b32_e32 v18, v18, v27
	ds_read_b128 v[18:21], v18
	v_mov_b32_e32 v159, v113
	v_or_b32_e32 v25, 1, v24
	s_waitcnt vmcnt(3)
	v_lshlrev_b32_e32 v22, 16, v6
	v_and_b32_e32 v23, 0xffff0000, v6
	s_waitcnt lgkmcnt(1)
	v_pk_mul_f32 v[14:15], v[14:15], v[22:23]
	s_nop 0
	v_cvt_pk_bf16_f32 v6, v14, v15
	v_lshlrev_b32_e32 v14, 16, v7
	v_and_b32_e32 v15, 0xffff0000, v7
	v_pk_mul_f32 v[14:15], v[16:17], v[14:15]
	s_nop 0
	v_cvt_pk_bf16_f32 v7, v14, v15
	v_lshlrev_b32_e32 v14, 16, v8
	v_and_b32_e32 v15, 0xffff0000, v8
	s_waitcnt lgkmcnt(0)
	v_pk_mul_f32 v[14:15], v[18:19], v[14:15]
	v_or_b32_e32 v18, 8, v55
	v_cvt_pk_bf16_f32 v8, v14, v15
	v_lshlrev_b32_e32 v14, 16, v9
	v_and_b32_e32 v15, 0xffff0000, v9
	v_pk_mul_f32 v[14:15], v[20:21], v[14:15]
	v_mov_b32_e32 v19, v5
	v_cvt_pk_bf16_f32 v9, v14, v15
	v_lshl_add_u64 v[14:15], s[54:55], 0, v[52:53]
	v_lshl_add_u64 v[14:15], v[14:15], 0, s[14:15]
	v_lshl_add_u64 v[14:15], v[14:15], 0, v[158:159]
	global_store_dwordx4 v[14:15], v[6:9], off
	s_waitcnt vmcnt(3)
	v_lshlrev_b32_e32 v20, 16, v10
	v_and_b32_e32 v21, 0xffff0000, v10
	v_lshl_or_b32 v6, v18, 8, v56
	v_bitop3_b32 v7, v55, v24, 8 bitop3:0x36
	v_bitop3_b32 v8, v55, v25, 8 bitop3:0x36
	v_lshl_or_b32 v7, v7, 4, v6
	v_lshl_or_b32 v14, v8, 4, v6
	ds_read_b128 v[6:9], v7
	ds_read_b128 v[14:17], v14
	v_lshlrev_b32_e32 v10, 16, v11
	v_and_b32_e32 v11, 0xffff0000, v11
	v_or_b32_e32 v18, v4, v18
	s_waitcnt lgkmcnt(1)
	v_pk_mul_f32 v[6:7], v[6:7], v[20:21]
	v_pk_mul_f32 v[8:9], v[8:9], v[10:11]
	v_cvt_pk_bf16_f32 v6, v6, v7
	v_cvt_pk_bf16_f32 v7, v8, v9
	v_lshlrev_b32_e32 v8, 16, v12
	v_and_b32_e32 v9, 0xffff0000, v12
	v_lshlrev_b32_e32 v10, 16, v13
	v_and_b32_e32 v11, 0xffff0000, v13
	s_waitcnt lgkmcnt(0)
	v_pk_mul_f32 v[8:9], v[14:15], v[8:9]
	v_pk_mul_f32 v[10:11], v[16:17], v[10:11]
	v_cvt_pk_bf16_f32 v8, v8, v9
	v_cvt_pk_bf16_f32 v9, v10, v11
	v_lshlrev_b64 v[10:11], 11, v[18:19]
	v_lshl_add_u64 v[10:11], s[54:55], 0, v[10:11]
	v_lshl_add_u64 v[10:11], v[10:11], 0, s[14:15]
	v_lshl_add_u64 v[10:11], v[10:11], 0, v[158:159]
	v_or_b32_e32 v14, 16, v55
	global_store_dwordx4 v[10:11], v[6:9], off
	s_waitcnt vmcnt(3)
	v_lshlrev_b32_e32 v16, 16, v48
	v_and_b32_e32 v17, 0xffff0000, v48
	v_lshl_or_b32 v6, v14, 8, v56
	v_or_b32_e32 v7, v6, v26
	v_or_b32_e32 v10, v6, v27
	ds_read_b128 v[6:9], v7
	ds_read_b128 v[10:13], v10
	v_or_b32_e32 v14, v4, v14
	v_mov_b32_e32 v15, v5
	s_waitcnt lgkmcnt(1)
	v_pk_mul_f32 v[6:7], v[6:7], v[16:17]
	v_lshlrev_b32_e32 v16, 16, v49
	v_and_b32_e32 v17, 0xffff0000, v49
	v_pk_mul_f32 v[8:9], v[8:9], v[16:17]
	v_cvt_pk_bf16_f32 v6, v6, v7
	v_cvt_pk_bf16_f32 v7, v8, v9
	v_lshlrev_b32_e32 v8, 16, v50
	v_and_b32_e32 v9, 0xffff0000, v50
	s_waitcnt lgkmcnt(0)
	v_pk_mul_f32 v[8:9], v[10:11], v[8:9]
	v_lshlrev_b32_e32 v10, 16, v51
	v_and_b32_e32 v11, 0xffff0000, v51
	v_pk_mul_f32 v[10:11], v[12:13], v[10:11]
	v_cvt_pk_bf16_f32 v8, v8, v9
	v_cvt_pk_bf16_f32 v9, v10, v11
	v_lshlrev_b64 v[10:11], 11, v[14:15]
	v_lshl_add_u64 v[10:11], s[54:55], 0, v[10:11]
	v_lshl_add_u64 v[10:11], v[10:11], 0, s[14:15]
	v_lshl_add_u64 v[10:11], v[10:11], 0, v[158:159]
	v_or_b32_e32 v14, 24, v55
	global_store_dwordx4 v[10:11], v[6:9], off
	v_or_b32_e32 v4, v4, v14
	s_waitcnt vmcnt(3)
	v_and_b32_e32 v15, 0xffff0000, v0
	v_lshl_or_b32 v6, v14, 8, v56
	v_bitop3_b32 v7, v14, v24, 15 bitop3:0x6c
	v_bitop3_b32 v8, v14, v25, 15 bitop3:0x6c
	v_lshl_or_b32 v7, v7, 4, v6
	v_lshl_or_b32 v10, v8, 4, v6
	ds_read_b128 v[6:9], v7
	ds_read_b128 v[10:13], v10
	v_lshlrev_b32_e32 v14, 16, v0
	v_lshlrev_b64 v[4:5], 11, v[4:5]
	v_lshl_add_u64 v[4:5], s[54:55], 0, v[4:5]
	s_waitcnt lgkmcnt(1)
	v_pk_mul_f32 v[6:7], v[6:7], v[14:15]
	v_lshl_add_u64 v[4:5], v[4:5], 0, s[14:15]
	v_cvt_pk_bf16_f32 v0, v6, v7
	v_lshlrev_b32_e32 v6, 16, v1
	v_and_b32_e32 v7, 0xffff0000, v1
	v_pk_mul_f32 v[6:7], v[8:9], v[6:7]
	v_lshl_add_u64 v[4:5], v[4:5], 0, v[158:159]
	v_cvt_pk_bf16_f32 v1, v6, v7
	v_lshlrev_b32_e32 v6, 16, v2
	v_and_b32_e32 v7, 0xffff0000, v2
	s_waitcnt lgkmcnt(0)
	v_pk_mul_f32 v[6:7], v[10:11], v[6:7]
	s_nop 0
	v_cvt_pk_bf16_f32 v2, v6, v7
	v_lshlrev_b32_e32 v6, 16, v3
	v_and_b32_e32 v7, 0xffff0000, v3
	v_pk_mul_f32 v[6:7], v[12:13], v[6:7]
	s_nop 0
	v_cvt_pk_bf16_f32 v3, v6, v7
	global_store_dwordx4 v[4:5], v[0:3], off
	s_and_saveexec_b64 s[4:5], s[16:17]
	s_cbranch_execz .LBB0_417
	ds_write_b32 v178, v170
	s_branch .LBB0_417

	.amdhsa_kernel _Z6mk_fwd6Paramsii
		.amdhsa_group_segment_fixed_size 131156
		.amdhsa_private_segment_fixed_size 0
		.amdhsa_kernarg_size 568
		.amdhsa_user_sgpr_count 2
		.amdhsa_user_sgpr_dispatch_ptr 0
		.amdhsa_user_sgpr_queue_ptr 0
		.amdhsa_user_sgpr_kernarg_segment_ptr 1
		.amdhsa_user_sgpr_dispatch_id 0
		.amdhsa_user_sgpr_kernarg_preload_length 0
		.amdhsa_user_sgpr_kernarg_preload_offset 0
		.amdhsa_user_sgpr_private_segment_size 0
		.amdhsa_uses_dynamic_stack 0
		.amdhsa_enable_private_segment 0
		.amdhsa_system_sgpr_workgroup_id_x 1
		.amdhsa_system_sgpr_workgroup_id_y 0
		.amdhsa_system_sgpr_workgroup_id_z 0
		.amdhsa_system_sgpr_workgroup_info 0
		.amdhsa_system_vgpr_workitem_id 2
		.amdhsa_next_free_vgpr 256
		.amdhsa_next_free_sgpr 102
		.amdhsa_accum_offset 256
		.amdhsa_reserve_vcc 1
		.amdhsa_float_round_mode_32 0
		.amdhsa_float_round_mode_16_64 0
		.amdhsa_float_denorm_mode_32 3
		.amdhsa_float_denorm_mode_16_64 3
		.amdhsa_dx10_clamp 1
		.amdhsa_ieee_mode 1
		.amdhsa_fp16_overflow 0
		.amdhsa_tg_split 0
		.amdhsa_exception_fp_ieee_invalid_op 0
		.amdhsa_exception_fp_denorm_src 0
		.amdhsa_exception_fp_ieee_div_zero 0
		.amdhsa_exception_fp_ieee_overflow 0
		.amdhsa_exception_fp_ieee_underflow 0
		.amdhsa_exception_fp_ieee_inexact 0
		.amdhsa_exception_int_div_zero 0
	.end_amdhsa_kernel

amdhsa.kernels:
  - .agpr_count:     0
    .args:
      - .offset:         0
        .size:           304
        .value_kind:     by_value
      - .offset:         304
        .size:           4
        .value_kind:     by_value
      - .offset:         308
        .size:           4
        .value_kind:     by_value
      - .offset:         312
        .size:           4
        .value_kind:     hidden_block_count_x
      - .offset:         316
        .size:           4
        .value_kind:     hidden_block_count_y
      - .offset:         320
        .size:           4
        .value_kind:     hidden_block_count_z
      - .offset:         324
        .size:           2
        .value_kind:     hidden_group_size_x
      - .offset:         326
        .size:           2
        .value_kind:     hidden_group_size_y
      - .offset:         328
        .size:           2
        .value_kind:     hidden_group_size_z
      - .offset:         330
        .size:           2
        .value_kind:     hidden_remainder_x
      - .offset:         332
        .size:           2
        .value_kind:     hidden_remainder_y
      - .offset:         334
        .size:           2
        .value_kind:     hidden_remainder_z
      - .offset:         352
        .size:           8
        .value_kind:     hidden_global_offset_x
      - .offset:         360
        .size:           8
        .value_kind:     hidden_global_offset_y
      - .offset:         368
        .size:           8
        .value_kind:     hidden_global_offset_z
      - .offset:         376
        .size:           2
        .value_kind:     hidden_grid_dims
      - .offset:         400
        .size:           8
        .value_kind:     hidden_multigrid_sync_arg
    .group_segment_fixed_size: 131156
    .kernarg_segment_align: 8
    .kernarg_segment_size: 568
    .language:       OpenCL C
    .language_version:
      - 2
      - 0
    .max_flat_workgroup_size: 512
    .name:           _Z6mk_fwd6Paramsii
    .private_segment_fixed_size: 0
    .sgpr_count:     108
    .sgpr_spill_count: 65
    .symbol:         _Z6mk_fwd6Paramsii.kd
    .uniform_work_group_size: 1
    .uses_dynamic_stack: false
    .vgpr_count:     256
    .vgpr_spill_count: 0
    .wavefront_size: 64
